# P0 x-rownorm hand-scheduled (3 rows in flight, gains hoisted) on top of v49
# baseline (speedup 1.0000x reference)
; __device__ __forceinline__ unsigned cvt_pk_bf16(float lo, float hi) { unsigned r; asm volatile("v_cvt_pk_bf16_f32 %0, %1, %2" : "=v"(r) : "v"(lo), "v"(hi)); return r; }
; __device__ __forceinline__ float dot4(f32x4 a) { return (a[0] * a[0] + a[1] * a[1]) + (a[2] * a[2] + a[3] * a[3]); }
; __device__ __forceinline__ void rownorm_bf16(const float* __restrict__ x, const float* __restrict__ g, bf16_t* __restrict__ out, int nrows) {
;   const int wave = threadIdx.x >> 6, lane = threadIdx.x & 63;
;   for (int row = blockIdx.x * 8 + wave; row < nrows; row += gridDim.x * 8) {
;     const f32x4* xr = (const f32x4*)(x + (size_t)row * DM); f32x4 v[8]; float ss = 0.f;
; #pragma unroll
;     for (int j = 0; j < 8; ++j) { v[j] = xr[lane + 64 * j]; ss += dot4(v[j]); }
;     ss = wave_sum(ss); const float r = rsqrtf(ss * (1.f / DM) + NORM_EPS);
; #pragma unroll
;     for (int j = 0; j < 8; ++j) { const f32x4 gv = ((const f32x4*)g)[lane + 64 * j], w = v[j] * gv * r; u32x2 pk; pk.x = cvt_pk_bf16(w[0], w[1]); pk.y = cvt_pk_bf16(w[2], w[3]);
;       *(u32x2*)(out + (size_t)row * DM + 4 * (lane + 64 * j)) = pk; }
;   }
; }
.LBB0_80:
	v_lshrrev_b32_e32 v0, 6, v187
	v_and_b32_e32 v52, 63, v187
	v_lshl_add_u32 v12, s14, 3, v0
	v_or_b32_e32 v0, 0x100, v52
	v_or_b32_e32 v1, 0x140, v52
	v_or_b32_e32 v2, 0x180, v52
	v_or_b32_e32 v3, 0x1c0, v52
	v_lshlrev_b32_e32 v13, 2, v52
	s_movk_i32 s0, 0x4000
	v_or_b32_e32 v4, 0x100, v13
	v_or_b32_e32 v5, 0x200, v13
	v_or_b32_e32 v6, 0x300, v13
	v_lshlrev_b32_e32 v7, 2, v0
	v_lshlrev_b32_e32 v8, 2, v1
	v_lshlrev_b32_e32 v9, 2, v2
	v_lshlrev_b32_e32 v10, 2, v3
	v_cmp_gt_i32_e32 vcc, s0, v12
	v_mov_b32_e32 v39, 0
	s_lshl_b32 s6, s78, 3
	v_lshlrev_b32_e32 v14, 4, v52
	v_lshlrev_b32_e32 v16, 4, v0
	v_lshlrev_b32_e32 v18, 4, v1
	v_lshlrev_b32_e32 v20, 4, v2
	v_lshlrev_b32_e32 v22, 4, v3
	v_lshlrev_b32_e32 v24, 1, v4
	v_lshlrev_b32_e32 v26, 1, v5
	v_lshlrev_b32_e32 v28, 1, v6
	v_lshlrev_b32_e32 v30, 1, v7
	v_lshlrev_b32_e32 v32, 1, v8
	v_lshlrev_b32_e32 v34, 1, v9
	v_lshlrev_b32_e32 v36, 1, v10
	s_and_saveexec_b64 s[0:1], vcc
	s_cbranch_execz .LBB0_83
	s_cmpk_eq_i32 s78, 0x100
	s_cbranch_scc0 .Lrn_orig
	v_mbcnt_lo_u32_b32 v232, -1, 0
	v_mbcnt_hi_u32_b32 v232, -1, v232
	v_lshlrev_b32_e32 v233, 4, v232
	v_add_u32_e32 v234, 0x1000, v233
	global_load_dwordx4 v[60:63], v233, s[42:43]
	global_load_dwordx4 v[64:67], v233, s[42:43] offset:1024
	global_load_dwordx4 v[68:71], v233, s[42:43] offset:2048
	global_load_dwordx4 v[72:75], v233, s[42:43] offset:3072
	global_load_dwordx4 v[76:79], v234, s[42:43]
	global_load_dwordx4 v[80:83], v234, s[42:43] offset:1024
	global_load_dwordx4 v[84:87], v234, s[42:43] offset:2048
	global_load_dwordx4 v[88:91], v234, s[42:43] offset:3072
	v_xor_b32_e32 v240, 32, v232
	v_lshlrev_b32_e32 v240, 2, v240
	v_xor_b32_e32 v241, 16, v232
	v_lshlrev_b32_e32 v241, 2, v241
	v_xor_b32_e32 v242, 8, v232
	v_lshlrev_b32_e32 v242, 2, v242
	v_xor_b32_e32 v243, 4, v232
	v_lshlrev_b32_e32 v243, 2, v243
	v_xor_b32_e32 v244, 2, v232
	v_lshlrev_b32_e32 v244, 2, v244
	v_xor_b32_e32 v245, 1, v232
	v_lshlrev_b32_e32 v245, 2, v245
	v_mov_b32_e32 v246, 0x358637bd
	s_add_u32 s2, s74, 0x7100000
	s_addc_u32 s3, s75, 0
	v_lshl_add_u32 v235, v12, 13, v233
	v_lshrrev_b32_e32 v237, 1, v233
	v_lshl_add_u32 v237, v12, 12, v237
	v_add_u32_e32 v236, 0x1000, v235
	global_load_dwordx4 v[92:95], v235, s[36:37]
	global_load_dwordx4 v[96:99], v235, s[36:37] offset:1024
	global_load_dwordx4 v[100:103], v235, s[36:37] offset:2048
	global_load_dwordx4 v[104:107], v235, s[36:37] offset:3072
	global_load_dwordx4 v[108:111], v236, s[36:37]
	global_load_dwordx4 v[112:115], v236, s[36:37] offset:1024
	global_load_dwordx4 v[116:119], v236, s[36:37] offset:2048
	global_load_dwordx4 v[120:123], v236, s[36:37] offset:3072
	v_add_u32_e32 v236, 0x1001000, v235
	v_add_u32_e32 v238, 0x1000000, v235
	global_load_dwordx4 v[124:127], v238, s[36:37]
	global_load_dwordx4 v[128:131], v238, s[36:37] offset:1024
	global_load_dwordx4 v[132:135], v238, s[36:37] offset:2048
	global_load_dwordx4 v[136:139], v238, s[36:37] offset:3072
	global_load_dwordx4 v[140:143], v236, s[36:37]
	global_load_dwordx4 v[144:147], v236, s[36:37] offset:1024
	global_load_dwordx4 v[148:151], v236, s[36:37] offset:2048
	global_load_dwordx4 v[156:159], v236, s[36:37] offset:3072
	v_add_u32_e32 v236, 0x2001000, v235
	v_add_u32_e32 v238, 0x2000000, v235
	global_load_dwordx4 v[160:163], v238, s[36:37]
	global_load_dwordx4 v[164:167], v238, s[36:37] offset:1024
	global_load_dwordx4 v[168:171], v238, s[36:37] offset:2048
	global_load_dwordx4 v[172:175], v238, s[36:37] offset:3072
	global_load_dwordx4 v[176:179], v236, s[36:37]
	global_load_dwordx4 v[180:183], v236, s[36:37] offset:1024
	global_load_dwordx4 v[196:199], v236, s[36:37] offset:2048
	global_load_dwordx4 v[200:203], v236, s[36:37] offset:3072
	s_waitcnt vmcnt(16)
	v_mul_f32_e32 v238, v92, v92
	v_mul_f32_e32 v239, v93, v93
	v_fmac_f32_e32 v238, v94, v94
	v_fmac_f32_e32 v239, v95, v95
	v_fmac_f32_e32 v238, v96, v96
	v_fmac_f32_e32 v239, v97, v97
	v_fmac_f32_e32 v238, v98, v98
	v_fmac_f32_e32 v239, v99, v99
	v_fmac_f32_e32 v238, v100, v100
	v_fmac_f32_e32 v239, v101, v101
	v_fmac_f32_e32 v238, v102, v102
	v_fmac_f32_e32 v239, v103, v103
	v_fmac_f32_e32 v238, v104, v104
	v_fmac_f32_e32 v239, v105, v105
	v_fmac_f32_e32 v238, v106, v106
	v_fmac_f32_e32 v239, v107, v107
	v_fmac_f32_e32 v238, v108, v108
	v_fmac_f32_e32 v239, v109, v109
	v_fmac_f32_e32 v238, v110, v110
	v_fmac_f32_e32 v239, v111, v111
	v_fmac_f32_e32 v238, v112, v112
	v_fmac_f32_e32 v239, v113, v113
	v_fmac_f32_e32 v238, v114, v114
	v_fmac_f32_e32 v239, v115, v115
	v_fmac_f32_e32 v238, v116, v116
	v_fmac_f32_e32 v239, v117, v117
	v_fmac_f32_e32 v238, v118, v118
	v_fmac_f32_e32 v239, v119, v119
	v_fmac_f32_e32 v238, v120, v120
	v_fmac_f32_e32 v239, v121, v121
	v_fmac_f32_e32 v238, v122, v122
	v_fmac_f32_e32 v239, v123, v123
	v_add_f32_e32 v238, v238, v239
	ds_bpermute_b32 v239, v240, v238
	v_pk_mul_f32 v[92:93], v[92:93], v[60:61]
	v_pk_mul_f32 v[94:95], v[94:95], v[62:63]
	v_pk_mul_f32 v[96:97], v[96:97], v[64:65]
	v_pk_mul_f32 v[98:99], v[98:99], v[66:67]
	v_pk_mul_f32 v[100:101], v[100:101], v[68:69]
	v_pk_mul_f32 v[102:103], v[102:103], v[70:71]
	v_pk_mul_f32 v[104:105], v[104:105], v[72:73]
	v_pk_mul_f32 v[106:107], v[106:107], v[74:75]
	v_pk_mul_f32 v[108:109], v[108:109], v[76:77]
	v_pk_mul_f32 v[110:111], v[110:111], v[78:79]
	v_pk_mul_f32 v[112:113], v[112:113], v[80:81]
	v_pk_mul_f32 v[114:115], v[114:115], v[82:83]
	v_pk_mul_f32 v[116:117], v[116:117], v[84:85]
	v_pk_mul_f32 v[118:119], v[118:119], v[86:87]
	v_pk_mul_f32 v[120:121], v[120:121], v[88:89]
	v_pk_mul_f32 v[122:123], v[122:123], v[90:91]
	s_waitcnt lgkmcnt(0)
	v_add_f32_e32 v238, v238, v239
	ds_bpermute_b32 v239, v241, v238
	s_waitcnt lgkmcnt(0)
; __device__ __forceinline__ unsigned cvt_pk_bf16(float lo, float hi) { unsigned r; asm volatile("v_cvt_pk_bf16_f32 %0, %1, %2" : "=v"(r) : "v"(lo), "v"(hi)); return r; }
; __device__ __forceinline__ float dot4(f32x4 a) { return (a[0] * a[0] + a[1] * a[1]) + (a[2] * a[2] + a[3] * a[3]); }
; __device__ __forceinline__ void rownorm_bf16(const float* __restrict__ x, const float* __restrict__ g, bf16_t* __restrict__ out, int nrows) {
;   const int wave = threadIdx.x >> 6, lane = threadIdx.x & 63;
;   for (int row = blockIdx.x * 8 + wave; row < nrows; row += gridDim.x * 8) {
;     const f32x4* xr = (const f32x4*)(x + (size_t)row * DM); f32x4 v[8]; float ss = 0.f;
; #pragma unroll
;     for (int j = 0; j < 8; ++j) { v[j] = xr[lane + 64 * j]; ss += dot4(v[j]); }
;     ss = wave_sum(ss); const float r = rsqrtf(ss * (1.f / DM) + NORM_EPS);
; #pragma unroll
;     for (int j = 0; j < 8; ++j) { const f32x4 gv = ((const f32x4*)g)[lane + 64 * j], w = v[j] * gv * r; u32x2 pk; pk.x = cvt_pk_bf16(w[0], w[1]); pk.y = cvt_pk_bf16(w[2], w[3]);
;       *(u32x2*)(out + (size_t)row * DM + 4 * (lane + 64 * j)) = pk; }
;   }
; }
	v_add_f32_e32 v238, v238, v239
	ds_bpermute_b32 v239, v242, v238
	s_waitcnt lgkmcnt(0)
	v_add_f32_e32 v238, v238, v239
	ds_bpermute_b32 v239, v243, v238
	s_waitcnt lgkmcnt(0)
	v_add_f32_e32 v238, v238, v239
	ds_bpermute_b32 v239, v244, v238
	s_waitcnt lgkmcnt(0)
	v_add_f32_e32 v238, v238, v239
	ds_bpermute_b32 v239, v245, v238
	s_waitcnt lgkmcnt(0)
	v_add_f32_e32 v238, v238, v239
	v_fmamk_f32 v238, v238, 0x3a000000, v246
	v_rsq_f32_e32 v238, v238
	s_nop 0
	v_mul_f32_e32 v92, v92, v238
	v_mul_f32_e32 v93, v93, v238
	v_mul_f32_e32 v94, v94, v238
	v_mul_f32_e32 v95, v95, v238
	v_cvt_pk_bf16_f32 v92, v92, v93
	v_cvt_pk_bf16_f32 v93, v94, v95
	global_store_dwordx2 v237, v[92:93], s[2:3]
	v_mul_f32_e32 v96, v96, v238
	v_mul_f32_e32 v97, v97, v238
	v_mul_f32_e32 v98, v98, v238
	v_mul_f32_e32 v99, v99, v238
	v_cvt_pk_bf16_f32 v96, v96, v97
	v_cvt_pk_bf16_f32 v97, v98, v99
	global_store_dwordx2 v237, v[96:97], s[2:3] offset:512
	v_mul_f32_e32 v100, v100, v238
	v_mul_f32_e32 v101, v101, v238
	v_mul_f32_e32 v102, v102, v238
	v_mul_f32_e32 v103, v103, v238
	v_cvt_pk_bf16_f32 v100, v100, v101
	v_cvt_pk_bf16_f32 v101, v102, v103
	global_store_dwordx2 v237, v[100:101], s[2:3] offset:1024
	v_mul_f32_e32 v104, v104, v238
	v_mul_f32_e32 v105, v105, v238
	v_mul_f32_e32 v106, v106, v238
	v_mul_f32_e32 v107, v107, v238
	v_cvt_pk_bf16_f32 v104, v104, v105
	v_cvt_pk_bf16_f32 v105, v106, v107
	global_store_dwordx2 v237, v[104:105], s[2:3] offset:1536
	v_mul_f32_e32 v108, v108, v238
	v_mul_f32_e32 v109, v109, v238
	v_mul_f32_e32 v110, v110, v238
	v_mul_f32_e32 v111, v111, v238
	v_cvt_pk_bf16_f32 v108, v108, v109
	v_cvt_pk_bf16_f32 v109, v110, v111
	global_store_dwordx2 v237, v[108:109], s[2:3] offset:2048
	v_mul_f32_e32 v112, v112, v238
	v_mul_f32_e32 v113, v113, v238
	v_mul_f32_e32 v114, v114, v238
	v_mul_f32_e32 v115, v115, v238
	v_cvt_pk_bf16_f32 v112, v112, v113
	v_cvt_pk_bf16_f32 v113, v114, v115
	global_store_dwordx2 v237, v[112:113], s[2:3] offset:2560
	v_mul_f32_e32 v116, v116, v238
	v_mul_f32_e32 v117, v117, v238
	v_mul_f32_e32 v118, v118, v238
	v_mul_f32_e32 v119, v119, v238
	v_cvt_pk_bf16_f32 v116, v116, v117
	v_cvt_pk_bf16_f32 v117, v118, v119
	global_store_dwordx2 v237, v[116:117], s[2:3] offset:3072
	v_mul_f32_e32 v120, v120, v238
	v_mul_f32_e32 v121, v121, v238
	v_mul_f32_e32 v122, v122, v238
	v_mul_f32_e32 v123, v123, v238
	v_cvt_pk_bf16_f32 v120, v120, v121
	v_cvt_pk_bf16_f32 v121, v122, v123
	global_store_dwordx2 v237, v[120:121], s[2:3] offset:3584
	v_add_u32_e32 v236, 0x3001000, v235
	v_add_u32_e32 v238, 0x3000000, v235
	global_load_dwordx4 v[92:95], v238, s[36:37]
	global_load_dwordx4 v[96:99], v238, s[36:37] offset:1024
	global_load_dwordx4 v[100:103], v238, s[36:37] offset:2048
	global_load_dwordx4 v[104:107], v238, s[36:37] offset:3072
	global_load_dwordx4 v[108:111], v236, s[36:37]
	global_load_dwordx4 v[112:115], v236, s[36:37] offset:1024
	global_load_dwordx4 v[116:119], v236, s[36:37] offset:2048
	global_load_dwordx4 v[120:123], v236, s[36:37] offset:3072
	s_waitcnt vmcnt(24)
	v_mul_f32_e32 v238, v124, v124
	v_mul_f32_e32 v239, v125, v125
	v_fmac_f32_e32 v238, v126, v126
	v_fmac_f32_e32 v239, v127, v127
	v_fmac_f32_e32 v238, v128, v128
	v_fmac_f32_e32 v239, v129, v129
	v_fmac_f32_e32 v238, v130, v130
	v_fmac_f32_e32 v239, v131, v131
	v_fmac_f32_e32 v238, v132, v132
	v_fmac_f32_e32 v239, v133, v133
	v_fmac_f32_e32 v238, v134, v134
	v_fmac_f32_e32 v239, v135, v135
	v_fmac_f32_e32 v238, v136, v136
	v_fmac_f32_e32 v239, v137, v137
	v_fmac_f32_e32 v238, v138, v138
	v_fmac_f32_e32 v239, v139, v139
	v_fmac_f32_e32 v238, v140, v140
	v_fmac_f32_e32 v239, v141, v141
	v_fmac_f32_e32 v238, v142, v142
	v_fmac_f32_e32 v239, v143, v143
	v_fmac_f32_e32 v238, v144, v144
	v_fmac_f32_e32 v239, v145, v145
	v_fmac_f32_e32 v238, v146, v146
	v_fmac_f32_e32 v239, v147, v147
	v_fmac_f32_e32 v238, v148, v148
	v_fmac_f32_e32 v239, v149, v149
	v_fmac_f32_e32 v238, v150, v150
	v_fmac_f32_e32 v239, v151, v151
	v_fmac_f32_e32 v238, v156, v156
	v_fmac_f32_e32 v239, v157, v157
	v_fmac_f32_e32 v238, v158, v158
	v_fmac_f32_e32 v239, v159, v159
	v_add_f32_e32 v238, v238, v239
	ds_bpermute_b32 v239, v240, v238
	v_pk_mul_f32 v[124:125], v[124:125], v[60:61]
	v_pk_mul_f32 v[126:127], v[126:127], v[62:63]
	v_pk_mul_f32 v[128:129], v[128:129], v[64:65]
	v_pk_mul_f32 v[130:131], v[130:131], v[66:67]
	v_pk_mul_f32 v[132:133], v[132:133], v[68:69]
	v_pk_mul_f32 v[134:135], v[134:135], v[70:71]
	v_pk_mul_f32 v[136:137], v[136:137], v[72:73]
	v_pk_mul_f32 v[138:139], v[138:139], v[74:75]
	v_pk_mul_f32 v[140:141], v[140:141], v[76:77]
	v_pk_mul_f32 v[142:143], v[142:143], v[78:79]
	v_pk_mul_f32 v[144:145], v[144:145], v[80:81]
	v_pk_mul_f32 v[146:147], v[146:147], v[82:83]
	v_pk_mul_f32 v[148:149], v[148:149], v[84:85]
	v_pk_mul_f32 v[150:151], v[150:151], v[86:87]
	v_pk_mul_f32 v[156:157], v[156:157], v[88:89]
	v_pk_mul_f32 v[158:159], v[158:159], v[90:91]
	s_waitcnt lgkmcnt(0)
	v_add_f32_e32 v238, v238, v239
	ds_bpermute_b32 v239, v241, v238
	s_waitcnt lgkmcnt(0)
	v_add_f32_e32 v238, v238, v239
	ds_bpermute_b32 v239, v242, v238
	s_waitcnt lgkmcnt(0)
	v_add_f32_e32 v238, v238, v239
	ds_bpermute_b32 v239, v243, v238
	s_waitcnt lgkmcnt(0)
	v_add_f32_e32 v238, v238, v239
	ds_bpermute_b32 v239, v244, v238
	s_waitcnt lgkmcnt(0)
	v_add_f32_e32 v238, v238, v239
	ds_bpermute_b32 v239, v245, v238
	s_waitcnt lgkmcnt(0)
; __device__ __forceinline__ unsigned cvt_pk_bf16(float lo, float hi) { unsigned r; asm volatile("v_cvt_pk_bf16_f32 %0, %1, %2" : "=v"(r) : "v"(lo), "v"(hi)); return r; }
; __device__ __forceinline__ float dot4(f32x4 a) { return (a[0] * a[0] + a[1] * a[1]) + (a[2] * a[2] + a[3] * a[3]); }
; __device__ __forceinline__ void rownorm_bf16(const float* __restrict__ x, const float* __restrict__ g, bf16_t* __restrict__ out, int nrows) {
;   const int wave = threadIdx.x >> 6, lane = threadIdx.x & 63;
;   for (int row = blockIdx.x * 8 + wave; row < nrows; row += gridDim.x * 8) {
;     const f32x4* xr = (const f32x4*)(x + (size_t)row * DM); f32x4 v[8]; float ss = 0.f;
; #pragma unroll
;     for (int j = 0; j < 8; ++j) { v[j] = xr[lane + 64 * j]; ss += dot4(v[j]); }
;     ss = wave_sum(ss); const float r = rsqrtf(ss * (1.f / DM) + NORM_EPS);
; #pragma unroll
;     for (int j = 0; j < 8; ++j) { const f32x4 gv = ((const f32x4*)g)[lane + 64 * j], w = v[j] * gv * r; u32x2 pk; pk.x = cvt_pk_bf16(w[0], w[1]); pk.y = cvt_pk_bf16(w[2], w[3]);
;       *(u32x2*)(out + (size_t)row * DM + 4 * (lane + 64 * j)) = pk; }
;   }
; }
	v_add_f32_e32 v238, v238, v239
	v_fmamk_f32 v238, v238, 0x3a000000, v246
	v_rsq_f32_e32 v238, v238
	s_nop 0
	v_add_u32_e32 v236, 0x800000, v237
	v_mul_f32_e32 v124, v124, v238
	v_mul_f32_e32 v125, v125, v238
	v_mul_f32_e32 v126, v126, v238
	v_mul_f32_e32 v127, v127, v238
	v_cvt_pk_bf16_f32 v124, v124, v125
	v_cvt_pk_bf16_f32 v125, v126, v127
	global_store_dwordx2 v236, v[124:125], s[2:3]
	v_mul_f32_e32 v128, v128, v238
	v_mul_f32_e32 v129, v129, v238
	v_mul_f32_e32 v130, v130, v238
	v_mul_f32_e32 v131, v131, v238
	v_cvt_pk_bf16_f32 v128, v128, v129
	v_cvt_pk_bf16_f32 v129, v130, v131
	global_store_dwordx2 v236, v[128:129], s[2:3] offset:512
	v_mul_f32_e32 v132, v132, v238
	v_mul_f32_e32 v133, v133, v238
	v_mul_f32_e32 v134, v134, v238
	v_mul_f32_e32 v135, v135, v238
	v_cvt_pk_bf16_f32 v132, v132, v133
	v_cvt_pk_bf16_f32 v133, v134, v135
	global_store_dwordx2 v236, v[132:133], s[2:3] offset:1024
	v_mul_f32_e32 v136, v136, v238
	v_mul_f32_e32 v137, v137, v238
	v_mul_f32_e32 v138, v138, v238
	v_mul_f32_e32 v139, v139, v238
	v_cvt_pk_bf16_f32 v136, v136, v137
	v_cvt_pk_bf16_f32 v137, v138, v139
	global_store_dwordx2 v236, v[136:137], s[2:3] offset:1536
	v_mul_f32_e32 v140, v140, v238
	v_mul_f32_e32 v141, v141, v238
	v_mul_f32_e32 v142, v142, v238
	v_mul_f32_e32 v143, v143, v238
	v_cvt_pk_bf16_f32 v140, v140, v141
	v_cvt_pk_bf16_f32 v141, v142, v143
	global_store_dwordx2 v236, v[140:141], s[2:3] offset:2048
	v_mul_f32_e32 v144, v144, v238
	v_mul_f32_e32 v145, v145, v238
	v_mul_f32_e32 v146, v146, v238
	v_mul_f32_e32 v147, v147, v238
	v_cvt_pk_bf16_f32 v144, v144, v145
	v_cvt_pk_bf16_f32 v145, v146, v147
	global_store_dwordx2 v236, v[144:145], s[2:3] offset:2560
	v_mul_f32_e32 v148, v148, v238
	v_mul_f32_e32 v149, v149, v238
	v_mul_f32_e32 v150, v150, v238
	v_mul_f32_e32 v151, v151, v238
	v_cvt_pk_bf16_f32 v148, v148, v149
	v_cvt_pk_bf16_f32 v149, v150, v151
	global_store_dwordx2 v236, v[148:149], s[2:3] offset:3072
	v_mul_f32_e32 v156, v156, v238
	v_mul_f32_e32 v157, v157, v238
	v_mul_f32_e32 v158, v158, v238
	v_mul_f32_e32 v159, v159, v238
	v_cvt_pk_bf16_f32 v156, v156, v157
	v_cvt_pk_bf16_f32 v157, v158, v159
	global_store_dwordx2 v236, v[156:157], s[2:3] offset:3584
	v_add_u32_e32 v236, 0x4001000, v235
	v_add_u32_e32 v238, 0x4000000, v235
	global_load_dwordx4 v[124:127], v238, s[36:37]
	global_load_dwordx4 v[128:131], v238, s[36:37] offset:1024
	global_load_dwordx4 v[132:135], v238, s[36:37] offset:2048
	global_load_dwordx4 v[136:139], v238, s[36:37] offset:3072
	global_load_dwordx4 v[140:143], v236, s[36:37]
	global_load_dwordx4 v[144:147], v236, s[36:37] offset:1024
	global_load_dwordx4 v[148:151], v236, s[36:37] offset:2048
	global_load_dwordx4 v[156:159], v236, s[36:37] offset:3072
	s_waitcnt vmcnt(32)
	v_mul_f32_e32 v238, v160, v160
	v_mul_f32_e32 v239, v161, v161
	v_fmac_f32_e32 v238, v162, v162
	v_fmac_f32_e32 v239, v163, v163
	v_fmac_f32_e32 v238, v164, v164
	v_fmac_f32_e32 v239, v165, v165
	v_fmac_f32_e32 v238, v166, v166
	v_fmac_f32_e32 v239, v167, v167
	v_fmac_f32_e32 v238, v168, v168
	v_fmac_f32_e32 v239, v169, v169
	v_fmac_f32_e32 v238, v170, v170
	v_fmac_f32_e32 v239, v171, v171
	v_fmac_f32_e32 v238, v172, v172
	v_fmac_f32_e32 v239, v173, v173
	v_fmac_f32_e32 v238, v174, v174
	v_fmac_f32_e32 v239, v175, v175
	v_fmac_f32_e32 v238, v176, v176
	v_fmac_f32_e32 v239, v177, v177
	v_fmac_f32_e32 v238, v178, v178
	v_fmac_f32_e32 v239, v179, v179
	v_fmac_f32_e32 v238, v180, v180
	v_fmac_f32_e32 v239, v181, v181
	v_fmac_f32_e32 v238, v182, v182
	v_fmac_f32_e32 v239, v183, v183
	v_fmac_f32_e32 v238, v196, v196
	v_fmac_f32_e32 v239, v197, v197
	v_fmac_f32_e32 v238, v198, v198
	v_fmac_f32_e32 v239, v199, v199
	v_fmac_f32_e32 v238, v200, v200
	v_fmac_f32_e32 v239, v201, v201
	v_fmac_f32_e32 v238, v202, v202
	v_fmac_f32_e32 v239, v203, v203
	v_add_f32_e32 v238, v238, v239
	ds_bpermute_b32 v239, v240, v238
	v_pk_mul_f32 v[160:161], v[160:161], v[60:61]
	v_pk_mul_f32 v[162:163], v[162:163], v[62:63]
	v_pk_mul_f32 v[164:165], v[164:165], v[64:65]
	v_pk_mul_f32 v[166:167], v[166:167], v[66:67]
	v_pk_mul_f32 v[168:169], v[168:169], v[68:69]
	v_pk_mul_f32 v[170:171], v[170:171], v[70:71]
	v_pk_mul_f32 v[172:173], v[172:173], v[72:73]
	v_pk_mul_f32 v[174:175], v[174:175], v[74:75]
	v_pk_mul_f32 v[176:177], v[176:177], v[76:77]
	v_pk_mul_f32 v[178:179], v[178:179], v[78:79]
	v_pk_mul_f32 v[180:181], v[180:181], v[80:81]
	v_pk_mul_f32 v[182:183], v[182:183], v[82:83]
	v_pk_mul_f32 v[196:197], v[196:197], v[84:85]
	v_pk_mul_f32 v[198:199], v[198:199], v[86:87]
	v_pk_mul_f32 v[200:201], v[200:201], v[88:89]
	v_pk_mul_f32 v[202:203], v[202:203], v[90:91]
	s_waitcnt lgkmcnt(0)
	v_add_f32_e32 v238, v238, v239
	ds_bpermute_b32 v239, v241, v238
	s_waitcnt lgkmcnt(0)
	v_add_f32_e32 v238, v238, v239
	ds_bpermute_b32 v239, v242, v238
	s_waitcnt lgkmcnt(0)
	v_add_f32_e32 v238, v238, v239
	ds_bpermute_b32 v239, v243, v238
	s_waitcnt lgkmcnt(0)
	v_add_f32_e32 v238, v238, v239
	ds_bpermute_b32 v239, v244, v238
	s_waitcnt lgkmcnt(0)
	v_add_f32_e32 v238, v238, v239
	ds_bpermute_b32 v239, v245, v238
	s_waitcnt lgkmcnt(0)
; __device__ __forceinline__ unsigned cvt_pk_bf16(float lo, float hi) { unsigned r; asm volatile("v_cvt_pk_bf16_f32 %0, %1, %2" : "=v"(r) : "v"(lo), "v"(hi)); return r; }
; __device__ __forceinline__ float dot4(f32x4 a) { return (a[0] * a[0] + a[1] * a[1]) + (a[2] * a[2] + a[3] * a[3]); }
; __device__ __forceinline__ void rownorm_bf16(const float* __restrict__ x, const float* __restrict__ g, bf16_t* __restrict__ out, int nrows) {
;   const int wave = threadIdx.x >> 6, lane = threadIdx.x & 63;
;   for (int row = blockIdx.x * 8 + wave; row < nrows; row += gridDim.x * 8) {
;     const f32x4* xr = (const f32x4*)(x + (size_t)row * DM); f32x4 v[8]; float ss = 0.f;
; #pragma unroll
;     for (int j = 0; j < 8; ++j) { v[j] = xr[lane + 64 * j]; ss += dot4(v[j]); }
;     ss = wave_sum(ss); const float r = rsqrtf(ss * (1.f / DM) + NORM_EPS);
; #pragma unroll
;     for (int j = 0; j < 8; ++j) { const f32x4 gv = ((const f32x4*)g)[lane + 64 * j], w = v[j] * gv * r; u32x2 pk; pk.x = cvt_pk_bf16(w[0], w[1]); pk.y = cvt_pk_bf16(w[2], w[3]);
;       *(u32x2*)(out + (size_t)row * DM + 4 * (lane + 64 * j)) = pk; }
;   }
; }
	v_add_f32_e32 v238, v238, v239
	v_fmamk_f32 v238, v238, 0x3a000000, v246
	v_rsq_f32_e32 v238, v238
	s_nop 0
	v_add_u32_e32 v236, 0x1000000, v237
	v_mul_f32_e32 v160, v160, v238
	v_mul_f32_e32 v161, v161, v238
	v_mul_f32_e32 v162, v162, v238
	v_mul_f32_e32 v163, v163, v238
	v_cvt_pk_bf16_f32 v160, v160, v161
	v_cvt_pk_bf16_f32 v161, v162, v163
	global_store_dwordx2 v236, v[160:161], s[2:3]
	v_mul_f32_e32 v164, v164, v238
	v_mul_f32_e32 v165, v165, v238
	v_mul_f32_e32 v166, v166, v238
	v_mul_f32_e32 v167, v167, v238
	v_cvt_pk_bf16_f32 v164, v164, v165
	v_cvt_pk_bf16_f32 v165, v166, v167
	global_store_dwordx2 v236, v[164:165], s[2:3] offset:512
	v_mul_f32_e32 v168, v168, v238
	v_mul_f32_e32 v169, v169, v238
	v_mul_f32_e32 v170, v170, v238
	v_mul_f32_e32 v171, v171, v238
	v_cvt_pk_bf16_f32 v168, v168, v169
	v_cvt_pk_bf16_f32 v169, v170, v171
	global_store_dwordx2 v236, v[168:169], s[2:3] offset:1024
	v_mul_f32_e32 v172, v172, v238
	v_mul_f32_e32 v173, v173, v238
	v_mul_f32_e32 v174, v174, v238
	v_mul_f32_e32 v175, v175, v238
	v_cvt_pk_bf16_f32 v172, v172, v173
	v_cvt_pk_bf16_f32 v173, v174, v175
	global_store_dwordx2 v236, v[172:173], s[2:3] offset:1536
	v_mul_f32_e32 v176, v176, v238
	v_mul_f32_e32 v177, v177, v238
	v_mul_f32_e32 v178, v178, v238
	v_mul_f32_e32 v179, v179, v238
	v_cvt_pk_bf16_f32 v176, v176, v177
	v_cvt_pk_bf16_f32 v177, v178, v179
	global_store_dwordx2 v236, v[176:177], s[2:3] offset:2048
	v_mul_f32_e32 v180, v180, v238
	v_mul_f32_e32 v181, v181, v238
	v_mul_f32_e32 v182, v182, v238
	v_mul_f32_e32 v183, v183, v238
	v_cvt_pk_bf16_f32 v180, v180, v181
	v_cvt_pk_bf16_f32 v181, v182, v183
	global_store_dwordx2 v236, v[180:181], s[2:3] offset:2560
	v_mul_f32_e32 v196, v196, v238
	v_mul_f32_e32 v197, v197, v238
	v_mul_f32_e32 v198, v198, v238
	v_mul_f32_e32 v199, v199, v238
	v_cvt_pk_bf16_f32 v196, v196, v197
	v_cvt_pk_bf16_f32 v197, v198, v199
	global_store_dwordx2 v236, v[196:197], s[2:3] offset:3072
	v_mul_f32_e32 v200, v200, v238
	v_mul_f32_e32 v201, v201, v238
	v_mul_f32_e32 v202, v202, v238
	v_mul_f32_e32 v203, v203, v238
	v_cvt_pk_bf16_f32 v200, v200, v201
	v_cvt_pk_bf16_f32 v201, v202, v203
	global_store_dwordx2 v236, v[200:201], s[2:3] offset:3584
	v_add_u32_e32 v236, 0x5001000, v235
	v_add_u32_e32 v238, 0x5000000, v235
	global_load_dwordx4 v[160:163], v238, s[36:37]
	global_load_dwordx4 v[164:167], v238, s[36:37] offset:1024
	global_load_dwordx4 v[168:171], v238, s[36:37] offset:2048
	global_load_dwordx4 v[172:175], v238, s[36:37] offset:3072
	global_load_dwordx4 v[176:179], v236, s[36:37]
	global_load_dwordx4 v[180:183], v236, s[36:37] offset:1024
	global_load_dwordx4 v[196:199], v236, s[36:37] offset:2048
	global_load_dwordx4 v[200:203], v236, s[36:37] offset:3072
	s_waitcnt vmcnt(32)
	v_mul_f32_e32 v238, v92, v92
	v_mul_f32_e32 v239, v93, v93
	v_fmac_f32_e32 v238, v94, v94
	v_fmac_f32_e32 v239, v95, v95
	v_fmac_f32_e32 v238, v96, v96
	v_fmac_f32_e32 v239, v97, v97
	v_fmac_f32_e32 v238, v98, v98
	v_fmac_f32_e32 v239, v99, v99
	v_fmac_f32_e32 v238, v100, v100
	v_fmac_f32_e32 v239, v101, v101
	v_fmac_f32_e32 v238, v102, v102
	v_fmac_f32_e32 v239, v103, v103
	v_fmac_f32_e32 v238, v104, v104
	v_fmac_f32_e32 v239, v105, v105
	v_fmac_f32_e32 v238, v106, v106
	v_fmac_f32_e32 v239, v107, v107
	v_fmac_f32_e32 v238, v108, v108
	v_fmac_f32_e32 v239, v109, v109
	v_fmac_f32_e32 v238, v110, v110
	v_fmac_f32_e32 v239, v111, v111
	v_fmac_f32_e32 v238, v112, v112
	v_fmac_f32_e32 v239, v113, v113
	v_fmac_f32_e32 v238, v114, v114
	v_fmac_f32_e32 v239, v115, v115
	v_fmac_f32_e32 v238, v116, v116
	v_fmac_f32_e32 v239, v117, v117
	v_fmac_f32_e32 v238, v118, v118
	v_fmac_f32_e32 v239, v119, v119
	v_fmac_f32_e32 v238, v120, v120
	v_fmac_f32_e32 v239, v121, v121
	v_fmac_f32_e32 v238, v122, v122
	v_fmac_f32_e32 v239, v123, v123
	v_add_f32_e32 v238, v238, v239
	ds_bpermute_b32 v239, v240, v238
	v_pk_mul_f32 v[92:93], v[92:93], v[60:61]
	v_pk_mul_f32 v[94:95], v[94:95], v[62:63]
	v_pk_mul_f32 v[96:97], v[96:97], v[64:65]
	v_pk_mul_f32 v[98:99], v[98:99], v[66:67]
	v_pk_mul_f32 v[100:101], v[100:101], v[68:69]
	v_pk_mul_f32 v[102:103], v[102:103], v[70:71]
	v_pk_mul_f32 v[104:105], v[104:105], v[72:73]
	v_pk_mul_f32 v[106:107], v[106:107], v[74:75]
	v_pk_mul_f32 v[108:109], v[108:109], v[76:77]
	v_pk_mul_f32 v[110:111], v[110:111], v[78:79]
	v_pk_mul_f32 v[112:113], v[112:113], v[80:81]
	v_pk_mul_f32 v[114:115], v[114:115], v[82:83]
	v_pk_mul_f32 v[116:117], v[116:117], v[84:85]
	v_pk_mul_f32 v[118:119], v[118:119], v[86:87]
	v_pk_mul_f32 v[120:121], v[120:121], v[88:89]
	v_pk_mul_f32 v[122:123], v[122:123], v[90:91]
	s_waitcnt lgkmcnt(0)
	v_add_f32_e32 v238, v238, v239
	ds_bpermute_b32 v239, v241, v238
	s_waitcnt lgkmcnt(0)
	v_add_f32_e32 v238, v238, v239
	ds_bpermute_b32 v239, v242, v238
	s_waitcnt lgkmcnt(0)
	v_add_f32_e32 v238, v238, v239
	ds_bpermute_b32 v239, v243, v238
	s_waitcnt lgkmcnt(0)
	v_add_f32_e32 v238, v238, v239
	ds_bpermute_b32 v239, v244, v238
	s_waitcnt lgkmcnt(0)
	v_add_f32_e32 v238, v238, v239
	ds_bpermute_b32 v239, v245, v238
	s_waitcnt lgkmcnt(0)
; __device__ __forceinline__ unsigned cvt_pk_bf16(float lo, float hi) { unsigned r; asm volatile("v_cvt_pk_bf16_f32 %0, %1, %2" : "=v"(r) : "v"(lo), "v"(hi)); return r; }
; __device__ __forceinline__ float dot4(f32x4 a) { return (a[0] * a[0] + a[1] * a[1]) + (a[2] * a[2] + a[3] * a[3]); }
; __device__ __forceinline__ void rownorm_bf16(const float* __restrict__ x, const float* __restrict__ g, bf16_t* __restrict__ out, int nrows) {
;   const int wave = threadIdx.x >> 6, lane = threadIdx.x & 63;
;   for (int row = blockIdx.x * 8 + wave; row < nrows; row += gridDim.x * 8) {
;     const f32x4* xr = (const f32x4*)(x + (size_t)row * DM); f32x4 v[8]; float ss = 0.f;
; #pragma unroll
;     for (int j = 0; j < 8; ++j) { v[j] = xr[lane + 64 * j]; ss += dot4(v[j]); }
;     ss = wave_sum(ss); const float r = rsqrtf(ss * (1.f / DM) + NORM_EPS);
; #pragma unroll
;     for (int j = 0; j < 8; ++j) { const f32x4 gv = ((const f32x4*)g)[lane + 64 * j], w = v[j] * gv * r; u32x2 pk; pk.x = cvt_pk_bf16(w[0], w[1]); pk.y = cvt_pk_bf16(w[2], w[3]);
;       *(u32x2*)(out + (size_t)row * DM + 4 * (lane + 64 * j)) = pk; }
;   }
; }
	v_add_f32_e32 v238, v238, v239
	v_fmamk_f32 v238, v238, 0x3a000000, v246
	v_rsq_f32_e32 v238, v238
	s_nop 0
	v_add_u32_e32 v236, 0x1800000, v237
	v_mul_f32_e32 v92, v92, v238
	v_mul_f32_e32 v93, v93, v238
	v_mul_f32_e32 v94, v94, v238
	v_mul_f32_e32 v95, v95, v238
	v_cvt_pk_bf16_f32 v92, v92, v93
	v_cvt_pk_bf16_f32 v93, v94, v95
	global_store_dwordx2 v236, v[92:93], s[2:3]
	v_mul_f32_e32 v96, v96, v238
	v_mul_f32_e32 v97, v97, v238
	v_mul_f32_e32 v98, v98, v238
	v_mul_f32_e32 v99, v99, v238
	v_cvt_pk_bf16_f32 v96, v96, v97
	v_cvt_pk_bf16_f32 v97, v98, v99
	global_store_dwordx2 v236, v[96:97], s[2:3] offset:512
	v_mul_f32_e32 v100, v100, v238
	v_mul_f32_e32 v101, v101, v238
	v_mul_f32_e32 v102, v102, v238
	v_mul_f32_e32 v103, v103, v238
	v_cvt_pk_bf16_f32 v100, v100, v101
	v_cvt_pk_bf16_f32 v101, v102, v103
	global_store_dwordx2 v236, v[100:101], s[2:3] offset:1024
	v_mul_f32_e32 v104, v104, v238
	v_mul_f32_e32 v105, v105, v238
	v_mul_f32_e32 v106, v106, v238
	v_mul_f32_e32 v107, v107, v238
	v_cvt_pk_bf16_f32 v104, v104, v105
	v_cvt_pk_bf16_f32 v105, v106, v107
	global_store_dwordx2 v236, v[104:105], s[2:3] offset:1536
	v_mul_f32_e32 v108, v108, v238
	v_mul_f32_e32 v109, v109, v238
	v_mul_f32_e32 v110, v110, v238
	v_mul_f32_e32 v111, v111, v238
	v_cvt_pk_bf16_f32 v108, v108, v109
	v_cvt_pk_bf16_f32 v109, v110, v111
	global_store_dwordx2 v236, v[108:109], s[2:3] offset:2048
	v_mul_f32_e32 v112, v112, v238
	v_mul_f32_e32 v113, v113, v238
	v_mul_f32_e32 v114, v114, v238
	v_mul_f32_e32 v115, v115, v238
	v_cvt_pk_bf16_f32 v112, v112, v113
	v_cvt_pk_bf16_f32 v113, v114, v115
	global_store_dwordx2 v236, v[112:113], s[2:3] offset:2560
	v_mul_f32_e32 v116, v116, v238
	v_mul_f32_e32 v117, v117, v238
	v_mul_f32_e32 v118, v118, v238
	v_mul_f32_e32 v119, v119, v238
	v_cvt_pk_bf16_f32 v116, v116, v117
	v_cvt_pk_bf16_f32 v117, v118, v119
	global_store_dwordx2 v236, v[116:117], s[2:3] offset:3072
	v_mul_f32_e32 v120, v120, v238
	v_mul_f32_e32 v121, v121, v238
	v_mul_f32_e32 v122, v122, v238
	v_mul_f32_e32 v123, v123, v238
	v_cvt_pk_bf16_f32 v120, v120, v121
	v_cvt_pk_bf16_f32 v121, v122, v123
	global_store_dwordx2 v236, v[120:121], s[2:3] offset:3584
	v_add_u32_e32 v236, 0x6001000, v235
	v_add_u32_e32 v238, 0x6000000, v235
	global_load_dwordx4 v[92:95], v238, s[36:37]
	global_load_dwordx4 v[96:99], v238, s[36:37] offset:1024
	global_load_dwordx4 v[100:103], v238, s[36:37] offset:2048
	global_load_dwordx4 v[104:107], v238, s[36:37] offset:3072
	global_load_dwordx4 v[108:111], v236, s[36:37]
	global_load_dwordx4 v[112:115], v236, s[36:37] offset:1024
	global_load_dwordx4 v[116:119], v236, s[36:37] offset:2048
	global_load_dwordx4 v[120:123], v236, s[36:37] offset:3072
	s_waitcnt vmcnt(32)
	v_mul_f32_e32 v238, v124, v124
	v_mul_f32_e32 v239, v125, v125
	v_fmac_f32_e32 v238, v126, v126
	v_fmac_f32_e32 v239, v127, v127
	v_fmac_f32_e32 v238, v128, v128
	v_fmac_f32_e32 v239, v129, v129
	v_fmac_f32_e32 v238, v130, v130
	v_fmac_f32_e32 v239, v131, v131
	v_fmac_f32_e32 v238, v132, v132
	v_fmac_f32_e32 v239, v133, v133
	v_fmac_f32_e32 v238, v134, v134
	v_fmac_f32_e32 v239, v135, v135
	v_fmac_f32_e32 v238, v136, v136
	v_fmac_f32_e32 v239, v137, v137
	v_fmac_f32_e32 v238, v138, v138
	v_fmac_f32_e32 v239, v139, v139
	v_fmac_f32_e32 v238, v140, v140
	v_fmac_f32_e32 v239, v141, v141
	v_fmac_f32_e32 v238, v142, v142
	v_fmac_f32_e32 v239, v143, v143
	v_fmac_f32_e32 v238, v144, v144
	v_fmac_f32_e32 v239, v145, v145
	v_fmac_f32_e32 v238, v146, v146
	v_fmac_f32_e32 v239, v147, v147
	v_fmac_f32_e32 v238, v148, v148
	v_fmac_f32_e32 v239, v149, v149
	v_fmac_f32_e32 v238, v150, v150
	v_fmac_f32_e32 v239, v151, v151
	v_fmac_f32_e32 v238, v156, v156
	v_fmac_f32_e32 v239, v157, v157
	v_fmac_f32_e32 v238, v158, v158
	v_fmac_f32_e32 v239, v159, v159
	v_add_f32_e32 v238, v238, v239
	ds_bpermute_b32 v239, v240, v238
	v_pk_mul_f32 v[124:125], v[124:125], v[60:61]
	v_pk_mul_f32 v[126:127], v[126:127], v[62:63]
	v_pk_mul_f32 v[128:129], v[128:129], v[64:65]
	v_pk_mul_f32 v[130:131], v[130:131], v[66:67]
	v_pk_mul_f32 v[132:133], v[132:133], v[68:69]
	v_pk_mul_f32 v[134:135], v[134:135], v[70:71]
	v_pk_mul_f32 v[136:137], v[136:137], v[72:73]
	v_pk_mul_f32 v[138:139], v[138:139], v[74:75]
	v_pk_mul_f32 v[140:141], v[140:141], v[76:77]
	v_pk_mul_f32 v[142:143], v[142:143], v[78:79]
	v_pk_mul_f32 v[144:145], v[144:145], v[80:81]
	v_pk_mul_f32 v[146:147], v[146:147], v[82:83]
	v_pk_mul_f32 v[148:149], v[148:149], v[84:85]
	v_pk_mul_f32 v[150:151], v[150:151], v[86:87]
	v_pk_mul_f32 v[156:157], v[156:157], v[88:89]
	v_pk_mul_f32 v[158:159], v[158:159], v[90:91]
	s_waitcnt lgkmcnt(0)
	v_add_f32_e32 v238, v238, v239
	ds_bpermute_b32 v239, v241, v238
	s_waitcnt lgkmcnt(0)
	v_add_f32_e32 v238, v238, v239
	ds_bpermute_b32 v239, v242, v238
	s_waitcnt lgkmcnt(0)
	v_add_f32_e32 v238, v238, v239
	ds_bpermute_b32 v239, v243, v238
	s_waitcnt lgkmcnt(0)
	v_add_f32_e32 v238, v238, v239
	ds_bpermute_b32 v239, v244, v238
	s_waitcnt lgkmcnt(0)
	v_add_f32_e32 v238, v238, v239
	ds_bpermute_b32 v239, v245, v238
	s_waitcnt lgkmcnt(0)
; __device__ __forceinline__ unsigned cvt_pk_bf16(float lo, float hi) { unsigned r; asm volatile("v_cvt_pk_bf16_f32 %0, %1, %2" : "=v"(r) : "v"(lo), "v"(hi)); return r; }
; __device__ __forceinline__ float dot4(f32x4 a) { return (a[0] * a[0] + a[1] * a[1]) + (a[2] * a[2] + a[3] * a[3]); }
; __device__ __forceinline__ void rownorm_bf16(const float* __restrict__ x, const float* __restrict__ g, bf16_t* __restrict__ out, int nrows) {
;   const int wave = threadIdx.x >> 6, lane = threadIdx.x & 63;
;   for (int row = blockIdx.x * 8 + wave; row < nrows; row += gridDim.x * 8) {
;     const f32x4* xr = (const f32x4*)(x + (size_t)row * DM); f32x4 v[8]; float ss = 0.f;
; #pragma unroll
;     for (int j = 0; j < 8; ++j) { v[j] = xr[lane + 64 * j]; ss += dot4(v[j]); }
;     ss = wave_sum(ss); const float r = rsqrtf(ss * (1.f / DM) + NORM_EPS);
; #pragma unroll
;     for (int j = 0; j < 8; ++j) { const f32x4 gv = ((const f32x4*)g)[lane + 64 * j], w = v[j] * gv * r; u32x2 pk; pk.x = cvt_pk_bf16(w[0], w[1]); pk.y = cvt_pk_bf16(w[2], w[3]);
;       *(u32x2*)(out + (size_t)row * DM + 4 * (lane + 64 * j)) = pk; }
;   }
; }
	v_add_f32_e32 v238, v238, v239
	v_fmamk_f32 v238, v238, 0x3a000000, v246
	v_rsq_f32_e32 v238, v238
	s_nop 0
	v_add_u32_e32 v236, 0x2000000, v237
	v_mul_f32_e32 v124, v124, v238
	v_mul_f32_e32 v125, v125, v238
	v_mul_f32_e32 v126, v126, v238
	v_mul_f32_e32 v127, v127, v238
	v_cvt_pk_bf16_f32 v124, v124, v125
	v_cvt_pk_bf16_f32 v125, v126, v127
	global_store_dwordx2 v236, v[124:125], s[2:3]
	v_mul_f32_e32 v128, v128, v238
	v_mul_f32_e32 v129, v129, v238
	v_mul_f32_e32 v130, v130, v238
	v_mul_f32_e32 v131, v131, v238
	v_cvt_pk_bf16_f32 v128, v128, v129
	v_cvt_pk_bf16_f32 v129, v130, v131
	global_store_dwordx2 v236, v[128:129], s[2:3] offset:512
	v_mul_f32_e32 v132, v132, v238
	v_mul_f32_e32 v133, v133, v238
	v_mul_f32_e32 v134, v134, v238
	v_mul_f32_e32 v135, v135, v238
	v_cvt_pk_bf16_f32 v132, v132, v133
	v_cvt_pk_bf16_f32 v133, v134, v135
	global_store_dwordx2 v236, v[132:133], s[2:3] offset:1024
	v_mul_f32_e32 v136, v136, v238
	v_mul_f32_e32 v137, v137, v238
	v_mul_f32_e32 v138, v138, v238
	v_mul_f32_e32 v139, v139, v238
	v_cvt_pk_bf16_f32 v136, v136, v137
	v_cvt_pk_bf16_f32 v137, v138, v139
	global_store_dwordx2 v236, v[136:137], s[2:3] offset:1536
	v_mul_f32_e32 v140, v140, v238
	v_mul_f32_e32 v141, v141, v238
	v_mul_f32_e32 v142, v142, v238
	v_mul_f32_e32 v143, v143, v238
	v_cvt_pk_bf16_f32 v140, v140, v141
	v_cvt_pk_bf16_f32 v141, v142, v143
	global_store_dwordx2 v236, v[140:141], s[2:3] offset:2048
	v_mul_f32_e32 v144, v144, v238
	v_mul_f32_e32 v145, v145, v238
	v_mul_f32_e32 v146, v146, v238
	v_mul_f32_e32 v147, v147, v238
	v_cvt_pk_bf16_f32 v144, v144, v145
	v_cvt_pk_bf16_f32 v145, v146, v147
	global_store_dwordx2 v236, v[144:145], s[2:3] offset:2560
	v_mul_f32_e32 v148, v148, v238
	v_mul_f32_e32 v149, v149, v238
	v_mul_f32_e32 v150, v150, v238
	v_mul_f32_e32 v151, v151, v238
	v_cvt_pk_bf16_f32 v148, v148, v149
	v_cvt_pk_bf16_f32 v149, v150, v151
	global_store_dwordx2 v236, v[148:149], s[2:3] offset:3072
	v_mul_f32_e32 v156, v156, v238
	v_mul_f32_e32 v157, v157, v238
	v_mul_f32_e32 v158, v158, v238
	v_mul_f32_e32 v159, v159, v238
	v_cvt_pk_bf16_f32 v156, v156, v157
	v_cvt_pk_bf16_f32 v157, v158, v159
	global_store_dwordx2 v236, v[156:157], s[2:3] offset:3584
	v_add_u32_e32 v236, 0x7001000, v235
	v_add_u32_e32 v238, 0x7000000, v235
	global_load_dwordx4 v[124:127], v238, s[36:37]
	global_load_dwordx4 v[128:131], v238, s[36:37] offset:1024
	global_load_dwordx4 v[132:135], v238, s[36:37] offset:2048
	global_load_dwordx4 v[136:139], v238, s[36:37] offset:3072
	global_load_dwordx4 v[140:143], v236, s[36:37]
	global_load_dwordx4 v[144:147], v236, s[36:37] offset:1024
	global_load_dwordx4 v[148:151], v236, s[36:37] offset:2048
	global_load_dwordx4 v[156:159], v236, s[36:37] offset:3072
	s_waitcnt vmcnt(32)
	v_mul_f32_e32 v238, v160, v160
	v_mul_f32_e32 v239, v161, v161
	v_fmac_f32_e32 v238, v162, v162
	v_fmac_f32_e32 v239, v163, v163
	v_fmac_f32_e32 v238, v164, v164
	v_fmac_f32_e32 v239, v165, v165
	v_fmac_f32_e32 v238, v166, v166
	v_fmac_f32_e32 v239, v167, v167
	v_fmac_f32_e32 v238, v168, v168
	v_fmac_f32_e32 v239, v169, v169
	v_fmac_f32_e32 v238, v170, v170
	v_fmac_f32_e32 v239, v171, v171
	v_fmac_f32_e32 v238, v172, v172
	v_fmac_f32_e32 v239, v173, v173
	v_fmac_f32_e32 v238, v174, v174
	v_fmac_f32_e32 v239, v175, v175
	v_fmac_f32_e32 v238, v176, v176
	v_fmac_f32_e32 v239, v177, v177
	v_fmac_f32_e32 v238, v178, v178
	v_fmac_f32_e32 v239, v179, v179
	v_fmac_f32_e32 v238, v180, v180
	v_fmac_f32_e32 v239, v181, v181
	v_fmac_f32_e32 v238, v182, v182
	v_fmac_f32_e32 v239, v183, v183
	v_fmac_f32_e32 v238, v196, v196
	v_fmac_f32_e32 v239, v197, v197
	v_fmac_f32_e32 v238, v198, v198
	v_fmac_f32_e32 v239, v199, v199
	v_fmac_f32_e32 v238, v200, v200
	v_fmac_f32_e32 v239, v201, v201
	v_fmac_f32_e32 v238, v202, v202
	v_fmac_f32_e32 v239, v203, v203
	v_add_f32_e32 v238, v238, v239
	ds_bpermute_b32 v239, v240, v238
	v_pk_mul_f32 v[160:161], v[160:161], v[60:61]
	v_pk_mul_f32 v[162:163], v[162:163], v[62:63]
	v_pk_mul_f32 v[164:165], v[164:165], v[64:65]
	v_pk_mul_f32 v[166:167], v[166:167], v[66:67]
	v_pk_mul_f32 v[168:169], v[168:169], v[68:69]
	v_pk_mul_f32 v[170:171], v[170:171], v[70:71]
	v_pk_mul_f32 v[172:173], v[172:173], v[72:73]
	v_pk_mul_f32 v[174:175], v[174:175], v[74:75]
	v_pk_mul_f32 v[176:177], v[176:177], v[76:77]
	v_pk_mul_f32 v[178:179], v[178:179], v[78:79]
	v_pk_mul_f32 v[180:181], v[180:181], v[80:81]
	v_pk_mul_f32 v[182:183], v[182:183], v[82:83]
	v_pk_mul_f32 v[196:197], v[196:197], v[84:85]
	v_pk_mul_f32 v[198:199], v[198:199], v[86:87]
	v_pk_mul_f32 v[200:201], v[200:201], v[88:89]
	v_pk_mul_f32 v[202:203], v[202:203], v[90:91]
	s_waitcnt lgkmcnt(0)
	v_add_f32_e32 v238, v238, v239
	ds_bpermute_b32 v239, v241, v238
	s_waitcnt lgkmcnt(0)
	v_add_f32_e32 v238, v238, v239
	ds_bpermute_b32 v239, v242, v238
	s_waitcnt lgkmcnt(0)
	v_add_f32_e32 v238, v238, v239
	ds_bpermute_b32 v239, v243, v238
	s_waitcnt lgkmcnt(0)
	v_add_f32_e32 v238, v238, v239
	ds_bpermute_b32 v239, v244, v238
	s_waitcnt lgkmcnt(0)
	v_add_f32_e32 v238, v238, v239
	ds_bpermute_b32 v239, v245, v238
	s_waitcnt lgkmcnt(0)
; __device__ __forceinline__ unsigned cvt_pk_bf16(float lo, float hi) { unsigned r; asm volatile("v_cvt_pk_bf16_f32 %0, %1, %2" : "=v"(r) : "v"(lo), "v"(hi)); return r; }
; __device__ __forceinline__ float dot4(f32x4 a) { return (a[0] * a[0] + a[1] * a[1]) + (a[2] * a[2] + a[3] * a[3]); }
; __device__ __forceinline__ void rownorm_bf16(const float* __restrict__ x, const float* __restrict__ g, bf16_t* __restrict__ out, int nrows) {
;   const int wave = threadIdx.x >> 6, lane = threadIdx.x & 63;
;   for (int row = blockIdx.x * 8 + wave; row < nrows; row += gridDim.x * 8) {
;     const f32x4* xr = (const f32x4*)(x + (size_t)row * DM); f32x4 v[8]; float ss = 0.f;
; #pragma unroll
;     for (int j = 0; j < 8; ++j) { v[j] = xr[lane + 64 * j]; ss += dot4(v[j]); }
;     ss = wave_sum(ss); const float r = rsqrtf(ss * (1.f / DM) + NORM_EPS);
; #pragma unroll
;     for (int j = 0; j < 8; ++j) { const f32x4 gv = ((const f32x4*)g)[lane + 64 * j], w = v[j] * gv * r; u32x2 pk; pk.x = cvt_pk_bf16(w[0], w[1]); pk.y = cvt_pk_bf16(w[2], w[3]);
;       *(u32x2*)(out + (size_t)row * DM + 4 * (lane + 64 * j)) = pk; }
;   }
; }
	v_add_f32_e32 v238, v238, v239
	v_fmamk_f32 v238, v238, 0x3a000000, v246
	v_rsq_f32_e32 v238, v238
	s_nop 0
	v_add_u32_e32 v236, 0x2800000, v237
	v_mul_f32_e32 v160, v160, v238
	v_mul_f32_e32 v161, v161, v238
	v_mul_f32_e32 v162, v162, v238
	v_mul_f32_e32 v163, v163, v238
	v_cvt_pk_bf16_f32 v160, v160, v161
	v_cvt_pk_bf16_f32 v161, v162, v163
	global_store_dwordx2 v236, v[160:161], s[2:3]
	v_mul_f32_e32 v164, v164, v238
	v_mul_f32_e32 v165, v165, v238
	v_mul_f32_e32 v166, v166, v238
	v_mul_f32_e32 v167, v167, v238
	v_cvt_pk_bf16_f32 v164, v164, v165
	v_cvt_pk_bf16_f32 v165, v166, v167
	global_store_dwordx2 v236, v[164:165], s[2:3] offset:512
	v_mul_f32_e32 v168, v168, v238
	v_mul_f32_e32 v169, v169, v238
	v_mul_f32_e32 v170, v170, v238
	v_mul_f32_e32 v171, v171, v238
	v_cvt_pk_bf16_f32 v168, v168, v169
	v_cvt_pk_bf16_f32 v169, v170, v171
	global_store_dwordx2 v236, v[168:169], s[2:3] offset:1024
	v_mul_f32_e32 v172, v172, v238
	v_mul_f32_e32 v173, v173, v238
	v_mul_f32_e32 v174, v174, v238
	v_mul_f32_e32 v175, v175, v238
	v_cvt_pk_bf16_f32 v172, v172, v173
	v_cvt_pk_bf16_f32 v173, v174, v175
	global_store_dwordx2 v236, v[172:173], s[2:3] offset:1536
	v_mul_f32_e32 v176, v176, v238
	v_mul_f32_e32 v177, v177, v238
	v_mul_f32_e32 v178, v178, v238
	v_mul_f32_e32 v179, v179, v238
	v_cvt_pk_bf16_f32 v176, v176, v177
	v_cvt_pk_bf16_f32 v177, v178, v179
	global_store_dwordx2 v236, v[176:177], s[2:3] offset:2048
	v_mul_f32_e32 v180, v180, v238
	v_mul_f32_e32 v181, v181, v238
	v_mul_f32_e32 v182, v182, v238
	v_mul_f32_e32 v183, v183, v238
	v_cvt_pk_bf16_f32 v180, v180, v181
	v_cvt_pk_bf16_f32 v181, v182, v183
	global_store_dwordx2 v236, v[180:181], s[2:3] offset:2560
	v_mul_f32_e32 v196, v196, v238
	v_mul_f32_e32 v197, v197, v238
	v_mul_f32_e32 v198, v198, v238
	v_mul_f32_e32 v199, v199, v238
	v_cvt_pk_bf16_f32 v196, v196, v197
	v_cvt_pk_bf16_f32 v197, v198, v199
	global_store_dwordx2 v236, v[196:197], s[2:3] offset:3072
	v_mul_f32_e32 v200, v200, v238
	v_mul_f32_e32 v201, v201, v238
	v_mul_f32_e32 v202, v202, v238
	v_mul_f32_e32 v203, v203, v238
	v_cvt_pk_bf16_f32 v200, v200, v201
	v_cvt_pk_bf16_f32 v201, v202, v203
	global_store_dwordx2 v236, v[200:201], s[2:3] offset:3584
	s_waitcnt vmcnt(24)
	v_mul_f32_e32 v238, v92, v92
	v_mul_f32_e32 v239, v93, v93
	v_fmac_f32_e32 v238, v94, v94
	v_fmac_f32_e32 v239, v95, v95
	v_fmac_f32_e32 v238, v96, v96
	v_fmac_f32_e32 v239, v97, v97
	v_fmac_f32_e32 v238, v98, v98
	v_fmac_f32_e32 v239, v99, v99
	v_fmac_f32_e32 v238, v100, v100
	v_fmac_f32_e32 v239, v101, v101
	v_fmac_f32_e32 v238, v102, v102
	v_fmac_f32_e32 v239, v103, v103
	v_fmac_f32_e32 v238, v104, v104
	v_fmac_f32_e32 v239, v105, v105
	v_fmac_f32_e32 v238, v106, v106
	v_fmac_f32_e32 v239, v107, v107
	v_fmac_f32_e32 v238, v108, v108
	v_fmac_f32_e32 v239, v109, v109
	v_fmac_f32_e32 v238, v110, v110
	v_fmac_f32_e32 v239, v111, v111
	v_fmac_f32_e32 v238, v112, v112
	v_fmac_f32_e32 v239, v113, v113
	v_fmac_f32_e32 v238, v114, v114
	v_fmac_f32_e32 v239, v115, v115
	v_fmac_f32_e32 v238, v116, v116
	v_fmac_f32_e32 v239, v117, v117
	v_fmac_f32_e32 v238, v118, v118
	v_fmac_f32_e32 v239, v119, v119
	v_fmac_f32_e32 v238, v120, v120
	v_fmac_f32_e32 v239, v121, v121
	v_fmac_f32_e32 v238, v122, v122
	v_fmac_f32_e32 v239, v123, v123
	v_add_f32_e32 v238, v238, v239
	ds_bpermute_b32 v239, v240, v238
	v_pk_mul_f32 v[92:93], v[92:93], v[60:61]
	v_pk_mul_f32 v[94:95], v[94:95], v[62:63]
	v_pk_mul_f32 v[96:97], v[96:97], v[64:65]
	v_pk_mul_f32 v[98:99], v[98:99], v[66:67]
	v_pk_mul_f32 v[100:101], v[100:101], v[68:69]
	v_pk_mul_f32 v[102:103], v[102:103], v[70:71]
	v_pk_mul_f32 v[104:105], v[104:105], v[72:73]
	v_pk_mul_f32 v[106:107], v[106:107], v[74:75]
	v_pk_mul_f32 v[108:109], v[108:109], v[76:77]
	v_pk_mul_f32 v[110:111], v[110:111], v[78:79]
	v_pk_mul_f32 v[112:113], v[112:113], v[80:81]
	v_pk_mul_f32 v[114:115], v[114:115], v[82:83]
	v_pk_mul_f32 v[116:117], v[116:117], v[84:85]
	v_pk_mul_f32 v[118:119], v[118:119], v[86:87]
	v_pk_mul_f32 v[120:121], v[120:121], v[88:89]
	v_pk_mul_f32 v[122:123], v[122:123], v[90:91]
	s_waitcnt lgkmcnt(0)
	v_add_f32_e32 v238, v238, v239
	ds_bpermute_b32 v239, v241, v238
	s_waitcnt lgkmcnt(0)
	v_add_f32_e32 v238, v238, v239
	ds_bpermute_b32 v239, v242, v238
	s_waitcnt lgkmcnt(0)
	v_add_f32_e32 v238, v238, v239
	ds_bpermute_b32 v239, v243, v238
	s_waitcnt lgkmcnt(0)
	v_add_f32_e32 v238, v238, v239
	ds_bpermute_b32 v239, v244, v238
	s_waitcnt lgkmcnt(0)
	v_add_f32_e32 v238, v238, v239
	ds_bpermute_b32 v239, v245, v238
	s_waitcnt lgkmcnt(0)
	v_add_f32_e32 v238, v238, v239
	v_fmamk_f32 v238, v238, 0x3a000000, v246
	v_rsq_f32_e32 v238, v238
	s_nop 0
	v_add_u32_e32 v236, 0x3000000, v237
	v_mul_f32_e32 v92, v92, v238
	v_mul_f32_e32 v93, v93, v238
	v_mul_f32_e32 v94, v94, v238
	v_mul_f32_e32 v95, v95, v238
	v_cvt_pk_bf16_f32 v92, v92, v93
	v_cvt_pk_bf16_f32 v93, v94, v95
	global_store_dwordx2 v236, v[92:93], s[2:3]
	v_mul_f32_e32 v96, v96, v238
	v_mul_f32_e32 v97, v97, v238
	v_mul_f32_e32 v98, v98, v238
	v_mul_f32_e32 v99, v99, v238
	v_cvt_pk_bf16_f32 v96, v96, v97
	v_cvt_pk_bf16_f32 v97, v98, v99
	global_store_dwordx2 v236, v[96:97], s[2:3] offset:512
	v_mul_f32_e32 v100, v100, v238
	v_mul_f32_e32 v101, v101, v238
	v_mul_f32_e32 v102, v102, v238
	v_mul_f32_e32 v103, v103, v238
	v_cvt_pk_bf16_f32 v100, v100, v101
	v_cvt_pk_bf16_f32 v101, v102, v103
	global_store_dwordx2 v236, v[100:101], s[2:3] offset:1024
	v_mul_f32_e32 v104, v104, v238
	v_mul_f32_e32 v105, v105, v238
	v_mul_f32_e32 v106, v106, v238
	v_mul_f32_e32 v107, v107, v238
	v_cvt_pk_bf16_f32 v104, v104, v105
	v_cvt_pk_bf16_f32 v105, v106, v107
	global_store_dwordx2 v236, v[104:105], s[2:3] offset:1536
	v_mul_f32_e32 v108, v108, v238
	v_mul_f32_e32 v109, v109, v238
	v_mul_f32_e32 v110, v110, v238
	v_mul_f32_e32 v111, v111, v238
	v_cvt_pk_bf16_f32 v108, v108, v109
	v_cvt_pk_bf16_f32 v109, v110, v111
	global_store_dwordx2 v236, v[108:109], s[2:3] offset:2048
	v_mul_f32_e32 v112, v112, v238
	v_mul_f32_e32 v113, v113, v238
	v_mul_f32_e32 v114, v114, v238
	v_mul_f32_e32 v115, v115, v238
	v_cvt_pk_bf16_f32 v112, v112, v113
	v_cvt_pk_bf16_f32 v113, v114, v115
	global_store_dwordx2 v236, v[112:113], s[2:3] offset:2560
	v_mul_f32_e32 v116, v116, v238
	v_mul_f32_e32 v117, v117, v238
	v_mul_f32_e32 v118, v118, v238
	v_mul_f32_e32 v119, v119, v238
	v_cvt_pk_bf16_f32 v116, v116, v117
	v_cvt_pk_bf16_f32 v117, v118, v119
	global_store_dwordx2 v236, v[116:117], s[2:3] offset:3072
	v_mul_f32_e32 v120, v120, v238
	v_mul_f32_e32 v121, v121, v238
	v_mul_f32_e32 v122, v122, v238
	v_mul_f32_e32 v123, v123, v238
	v_cvt_pk_bf16_f32 v120, v120, v121
	v_cvt_pk_bf16_f32 v121, v122, v123
	global_store_dwordx2 v236, v[120:121], s[2:3] offset:3584
	s_waitcnt vmcnt(16)
; __device__ __forceinline__ unsigned cvt_pk_bf16(float lo, float hi) { unsigned r; asm volatile("v_cvt_pk_bf16_f32 %0, %1, %2" : "=v"(r) : "v"(lo), "v"(hi)); return r; }
; __device__ __forceinline__ float dot4(f32x4 a) { return (a[0] * a[0] + a[1] * a[1]) + (a[2] * a[2] + a[3] * a[3]); }
; __device__ __forceinline__ void rownorm_bf16(const float* __restrict__ x, const float* __restrict__ g, bf16_t* __restrict__ out, int nrows) {
;   const int wave = threadIdx.x >> 6, lane = threadIdx.x & 63;
;   for (int row = blockIdx.x * 8 + wave; row < nrows; row += gridDim.x * 8) {
;     const f32x4* xr = (const f32x4*)(x + (size_t)row * DM); f32x4 v[8]; float ss = 0.f;
; #pragma unroll
;     for (int j = 0; j < 8; ++j) { v[j] = xr[lane + 64 * j]; ss += dot4(v[j]); }
;     ss = wave_sum(ss); const float r = rsqrtf(ss * (1.f / DM) + NORM_EPS);
; #pragma unroll
;     for (int j = 0; j < 8; ++j) { const f32x4 gv = ((const f32x4*)g)[lane + 64 * j], w = v[j] * gv * r; u32x2 pk; pk.x = cvt_pk_bf16(w[0], w[1]); pk.y = cvt_pk_bf16(w[2], w[3]);
;       *(u32x2*)(out + (size_t)row * DM + 4 * (lane + 64 * j)) = pk; }
;   }
; }
	v_mul_f32_e32 v238, v124, v124
	v_mul_f32_e32 v239, v125, v125
	v_fmac_f32_e32 v238, v126, v126
	v_fmac_f32_e32 v239, v127, v127
	v_fmac_f32_e32 v238, v128, v128
	v_fmac_f32_e32 v239, v129, v129
	v_fmac_f32_e32 v238, v130, v130
	v_fmac_f32_e32 v239, v131, v131
	v_fmac_f32_e32 v238, v132, v132
	v_fmac_f32_e32 v239, v133, v133
	v_fmac_f32_e32 v238, v134, v134
	v_fmac_f32_e32 v239, v135, v135
	v_fmac_f32_e32 v238, v136, v136
	v_fmac_f32_e32 v239, v137, v137
	v_fmac_f32_e32 v238, v138, v138
	v_fmac_f32_e32 v239, v139, v139
	v_fmac_f32_e32 v238, v140, v140
	v_fmac_f32_e32 v239, v141, v141
	v_fmac_f32_e32 v238, v142, v142
	v_fmac_f32_e32 v239, v143, v143
	v_fmac_f32_e32 v238, v144, v144
	v_fmac_f32_e32 v239, v145, v145
	v_fmac_f32_e32 v238, v146, v146
	v_fmac_f32_e32 v239, v147, v147
	v_fmac_f32_e32 v238, v148, v148
	v_fmac_f32_e32 v239, v149, v149
	v_fmac_f32_e32 v238, v150, v150
	v_fmac_f32_e32 v239, v151, v151
	v_fmac_f32_e32 v238, v156, v156
	v_fmac_f32_e32 v239, v157, v157
	v_fmac_f32_e32 v238, v158, v158
	v_fmac_f32_e32 v239, v159, v159
	v_add_f32_e32 v238, v238, v239
	ds_bpermute_b32 v239, v240, v238
	v_pk_mul_f32 v[124:125], v[124:125], v[60:61]
	v_pk_mul_f32 v[126:127], v[126:127], v[62:63]
	v_pk_mul_f32 v[128:129], v[128:129], v[64:65]
	v_pk_mul_f32 v[130:131], v[130:131], v[66:67]
	v_pk_mul_f32 v[132:133], v[132:133], v[68:69]
	v_pk_mul_f32 v[134:135], v[134:135], v[70:71]
	v_pk_mul_f32 v[136:137], v[136:137], v[72:73]
	v_pk_mul_f32 v[138:139], v[138:139], v[74:75]
	v_pk_mul_f32 v[140:141], v[140:141], v[76:77]
	v_pk_mul_f32 v[142:143], v[142:143], v[78:79]
	v_pk_mul_f32 v[144:145], v[144:145], v[80:81]
	v_pk_mul_f32 v[146:147], v[146:147], v[82:83]
	v_pk_mul_f32 v[148:149], v[148:149], v[84:85]
	v_pk_mul_f32 v[150:151], v[150:151], v[86:87]
	v_pk_mul_f32 v[156:157], v[156:157], v[88:89]
	v_pk_mul_f32 v[158:159], v[158:159], v[90:91]
	s_waitcnt lgkmcnt(0)
	v_add_f32_e32 v238, v238, v239
	ds_bpermute_b32 v239, v241, v238
	s_waitcnt lgkmcnt(0)
	v_add_f32_e32 v238, v238, v239
	ds_bpermute_b32 v239, v242, v238
	s_waitcnt lgkmcnt(0)
	v_add_f32_e32 v238, v238, v239
	ds_bpermute_b32 v239, v243, v238
	s_waitcnt lgkmcnt(0)
	v_add_f32_e32 v238, v238, v239
	ds_bpermute_b32 v239, v244, v238
	s_waitcnt lgkmcnt(0)
	v_add_f32_e32 v238, v238, v239
	ds_bpermute_b32 v239, v245, v238
	s_waitcnt lgkmcnt(0)
	v_add_f32_e32 v238, v238, v239
	v_fmamk_f32 v238, v238, 0x3a000000, v246
	v_rsq_f32_e32 v238, v238
	s_nop 0
	v_add_u32_e32 v236, 0x3800000, v237
	v_mul_f32_e32 v124, v124, v238
	v_mul_f32_e32 v125, v125, v238
	v_mul_f32_e32 v126, v126, v238
	v_mul_f32_e32 v127, v127, v238
	v_cvt_pk_bf16_f32 v124, v124, v125
	v_cvt_pk_bf16_f32 v125, v126, v127
	global_store_dwordx2 v236, v[124:125], s[2:3]
	v_mul_f32_e32 v128, v128, v238
	v_mul_f32_e32 v129, v129, v238
	v_mul_f32_e32 v130, v130, v238
	v_mul_f32_e32 v131, v131, v238
	v_cvt_pk_bf16_f32 v128, v128, v129
	v_cvt_pk_bf16_f32 v129, v130, v131
	global_store_dwordx2 v236, v[128:129], s[2:3] offset:512
	v_mul_f32_e32 v132, v132, v238
	v_mul_f32_e32 v133, v133, v238
	v_mul_f32_e32 v134, v134, v238
	v_mul_f32_e32 v135, v135, v238
	v_cvt_pk_bf16_f32 v132, v132, v133
	v_cvt_pk_bf16_f32 v133, v134, v135
	global_store_dwordx2 v236, v[132:133], s[2:3] offset:1024
	v_mul_f32_e32 v136, v136, v238
	v_mul_f32_e32 v137, v137, v238
	v_mul_f32_e32 v138, v138, v238
	v_mul_f32_e32 v139, v139, v238
	v_cvt_pk_bf16_f32 v136, v136, v137
	v_cvt_pk_bf16_f32 v137, v138, v139
	global_store_dwordx2 v236, v[136:137], s[2:3] offset:1536
	v_mul_f32_e32 v140, v140, v238
	v_mul_f32_e32 v141, v141, v238
	v_mul_f32_e32 v142, v142, v238
	v_mul_f32_e32 v143, v143, v238
	v_cvt_pk_bf16_f32 v140, v140, v141
	v_cvt_pk_bf16_f32 v141, v142, v143
	global_store_dwordx2 v236, v[140:141], s[2:3] offset:2048
	v_mul_f32_e32 v144, v144, v238
	v_mul_f32_e32 v145, v145, v238
	v_mul_f32_e32 v146, v146, v238
	v_mul_f32_e32 v147, v147, v238
	v_cvt_pk_bf16_f32 v144, v144, v145
	v_cvt_pk_bf16_f32 v145, v146, v147
	global_store_dwordx2 v236, v[144:145], s[2:3] offset:2560
	v_mul_f32_e32 v148, v148, v238
	v_mul_f32_e32 v149, v149, v238
	v_mul_f32_e32 v150, v150, v238
	v_mul_f32_e32 v151, v151, v238
	v_cvt_pk_bf16_f32 v148, v148, v149
	v_cvt_pk_bf16_f32 v149, v150, v151
	global_store_dwordx2 v236, v[148:149], s[2:3] offset:3072
	v_mul_f32_e32 v156, v156, v238
	v_mul_f32_e32 v157, v157, v238
	v_mul_f32_e32 v158, v158, v238
	v_mul_f32_e32 v159, v159, v238
	v_cvt_pk_bf16_f32 v156, v156, v157
	v_cvt_pk_bf16_f32 v157, v158, v159
	global_store_dwordx2 v236, v[156:157], s[2:3] offset:3584
	s_branch .LBB0_83
.Lrn_orig:
	global_load_dwordx4 v[0:3], v14, s[42:43]
	v_mbcnt_lo_u32_b32 v4, -1, 0
	v_mbcnt_hi_u32_b32 v4, -1, v4
	v_and_b32_e32 v5, 64, v4
	v_add_u32_e32 v5, 64, v5
	v_xor_b32_e32 v6, 32, v4
	v_cmp_lt_i32_e32 vcc, v6, v5
	s_add_u32 s2, s74, 0x7100000
	v_mov_b32_e32 v15, v39
	v_cndmask_b32_e32 v6, v4, v6, vcc
	v_lshlrev_b32_e32 v53, 2, v6
	v_xor_b32_e32 v6, 16, v4
	v_cmp_lt_i32_e32 vcc, v6, v5
	v_mov_b32_e32 v17, v39
	v_mov_b32_e32 v19, v39
	v_cndmask_b32_e32 v6, v4, v6, vcc
	v_lshlrev_b32_e32 v54, 2, v6
	v_xor_b32_e32 v6, 8, v4
	v_cmp_lt_i32_e32 vcc, v6, v5
	v_mov_b32_e32 v21, v39
	v_mov_b32_e32 v23, v39
	v_cndmask_b32_e32 v6, v4, v6, vcc
	v_lshlrev_b32_e32 v55, 2, v6
	v_xor_b32_e32 v6, 4, v4
	v_cmp_lt_i32_e32 vcc, v6, v5
	s_addc_u32 s3, s75, 0
	v_lshl_add_u64 v[40:41], s[42:43], 0, v[14:15]
	v_cndmask_b32_e32 v6, v4, v6, vcc
	v_lshlrev_b32_e32 v56, 2, v6
	v_xor_b32_e32 v6, 2, v4
	v_cmp_lt_i32_e32 vcc, v6, v5
	v_lshl_add_u64 v[42:43], s[42:43], 0, v[16:17]
	v_lshl_add_u64 v[44:45], s[42:43], 0, v[18:19]
	v_cndmask_b32_e32 v6, v4, v6, vcc
	v_lshlrev_b32_e32 v57, 2, v6
	v_xor_b32_e32 v6, 1, v4
	v_cmp_lt_i32_e32 vcc, v6, v5
	v_lshl_add_u64 v[46:47], s[42:43], 0, v[20:21]
	v_lshl_add_u64 v[48:49], s[42:43], 0, v[22:23]
	v_cndmask_b32_e32 v4, v4, v6, vcc
	v_lshlrev_b32_e32 v58, 2, v4
	s_mov_b64 s[4:5], 0
	v_mov_b32_e32 v59, 0x358637bd
	s_mov_b32 s7, 0x800000
	s_movk_i32 s15, 0x3fff
	v_mov_b32_e32 v50, v12
